# ret_out: per-unit Q fragment loads issued before the unit barrier
# speedup vs baseline: 1.0045x; 1.0021x over previous
; __device__ __forceinline__ int opaque_bid() { int b = blockIdx.x; asm volatile("" : "+s"(b)); return b; }
; __device__ __forceinline__ void ret_out_phase(const bf16* Z, const bf16* SP, bf16* MIX, unsigned char* lds) {
;     ...
;     for (int u = opaque_bid(); u < 2048; u += gridDim.x) {
;         const int b = u >> 10, h = (u >> 7) & 7, n = u & 127; const size_t rowbase = (size_t)b * SEQ + n * 128;
;         const float lg = log1pf(-exp2f(-5.f - (float)h));
;         __syncthreads();
; #pragma unroll
;         for (int it = 0; it < 2; ++it) { const int ci = tid + it * NTHR, j = ci >> 3, c8 = (ci & 7) * 8;
;             *(u32x4*)(Ks + j * 72 + c8) = fk_[it]; *(u32x4*)(Vs + j * 72 + c8) = fv_[it];
;             *(u32x2*)(Ss + (ci >> 4) * 72 + (ci & 15) * 4) = fs_[it]; }
;         bf16x8 qf[2];
; #pragma unroll
;         for (int ks = 0; ks < 2; ++ks) qf[ks] = *(const bf16x8*)(Z + (rowbase + 16 * wave + r16) * EVEN_IN + h * 64 + 32 * ks + q4 * 8);
;         __syncthreads();
;         { const int un = u + (int)gridDim.x; if (un < 2048) RO_FETCH(un); }
.LBB0_588:
	s_bfe_u32 s97, s88, 0x30007
	v_cvt_f32_ubyte0_e32 v18, s97
	s_ashr_i32 s82, s88, 10
	v_sub_f32_e32 v26, 0xc0a00000, v18
	s_mov_b32 s84, 0xc2fc0000
	s_ashr_i32 s83, s82, 31
	s_and_b32 s86, s96, 0x3f80
	v_cmp_gt_f32_e32 vcc, s84, v26
	s_and_b64 s[84:85], vcc, exec
	s_cselect_b32 s87, 0xffffffc0, 0
	s_lshl_b64 s[84:85], s[82:83], 14
	s_or_b32 s84, s84, s86
	v_lshl_add_u64 v[18:19], v[70:71], 0, s[84:85]
	v_mov_b64_e32 v[20:21], s[94:95]
	v_mad_u64_u32 v[20:21], s[82:83], v18, s89, v[20:21]
	v_mov_b32_e32 v18, v21
	v_mad_u64_u32 v[18:19], s[82:83], v19, s89, v[18:19]
	v_mov_b32_e32 v21, v18
	s_lshl_b32 s16, s97, 7
	v_lshl_add_u64 v[18:19], v[20:21], 0, s[16:17]
	v_lshl_add_u64 v[18:19], v[18:19], 0, v[0:1]
	global_load_dwordx4 v[22:25], v[18:19], off
	s_nop 0
	global_load_dwordx4 v[18:21], v[18:19], off offset:64
	s_barrier
	v_cndmask_b32_e32 v27, 0, v169, vcc
	v_add_f32_e32 v26, v26, v27
	v_exp_f32_e32 v26, v26
	s_mov_b32 s82, 0x3f2aaaab
	s_mov_b32 s21, s17
	s_waitcnt vmcnt(7)
	ds_write_b128 v78, v[6:9] offset:18432
	s_waitcnt vmcnt(6)
	ds_write_b128 v78, v[2:5] offset:36864
	s_waitcnt vmcnt(3)
	ds_write_b64 v127, v[64:65] offset:55296
	ds_write_b128 v80, v[14:17] offset:18432
	ds_write_b128 v80, v[10:13] offset:36864
	s_waitcnt vmcnt(2)
	ds_write_b64 v128, v[66:67] offset:55296
	v_ldexp_f32 v89, v26, s87
	v_readlane_b32 s86, v240, 58
	s_add_i32 s88, s88, s86
	v_sub_f32_e32 v133, 1.0, v89
	s_cmpk_gt_i32 s88, 0x7ff
	v_frexp_mant_f32_e32 v26, v133
	s_cselect_b64 s[90:91], -1, 0
	v_cmp_gt_f32_e64 s[82:83], s82, v26
	s_and_b64 vcc, exec, s[90:91]
	s_waitcnt lgkmcnt(0)
	s_barrier
	v_readlane_b32 s87, v240, 59
	s_cbranch_vccnz .LBB0_590
	s_ashr_i32 s86, s88, 10
	v_readlane_b32 s89, v240, 40
	s_ashr_i32 s87, s86, 31
	s_add_i32 s89, s89, s96
	s_lshl_b64 s[86:87], s[86:87], 14
	s_and_b32 s89, s89, 0x3f80
	s_or_b32 s86, s86, s89
	s_mov_b32 s17, s21
	s_and_b32 s16, s88, 0x380
	s_ashr_i32 s89, s88, 31
	v_lshl_add_u64 v[10:11], v[72:73], 0, s[16:17]
	s_lshl_b64 vcc, s[88:89], 13
	v_lshl_add_u64 v[2:3], s[86:87], 0, v[58:59]
	s_movk_i32 s89, 0x1e00
	v_lshl_add_u64 v[12:13], s[86:87], 0, v[62:63]
	v_lshl_add_u64 v[26:27], v[74:75], 0, vcc
	v_mad_u64_u32 v[4:5], vcc, v2, s89, v[10:11]
	v_mad_u64_u32 v[10:11], s[86:87], v12, s89, v[10:11]
	v_mad_i32_i24 v5, v3, s89, v5
	v_lshl_add_u64 v[28:29], v[60:61], 1, v[26:27]
	v_mad_i32_i24 v11, v13, s89, v11
	global_load_dwordx4 v[6:9], v[4:5], off offset:1024
	s_nop 0
	global_load_dwordx4 v[2:5], v[4:5], off offset:2048
	s_nop 0
	global_load_dwordx4 v[14:17], v[10:11], off offset:1024
	s_nop 0
	global_load_dwordx4 v[10:13], v[10:11], off offset:2048
	v_lshl_add_u64 v[26:27], v[82:83], 1, v[26:27]
	global_load_dwordx2 v[64:65], v[28:29], off
	global_load_dwordx2 v[66:67], v[26:27], off
